# isel: L2 warm-up loads for the next indexer item issued at the start of the top-k selection
# speedup vs baseline: 1.0415x; 1.0012x over previous
.LBB0_335:
	s_add_i32 s29, s0, s29
	s_lshl_b32 s0, s0, 14
	s_ashr_i32 s14, s29, 6
	s_add_i32 s34, s0, 0
	s_cmp_gt_i32 s14, -1
	s_cselect_b64 s[30:31], -1, 0
	s_waitcnt vmcnt(1)
	v_mov_b32_e32 v4, 0
	s_and_b64 vcc, exec, s[30:31]
	v_mov_b32_e32 v0, 0
	s_waitcnt vmcnt(0)
	v_mov_b32_e32 v6, 0
	v_mov_b32_e32 v5, 0
	v_mov_b32_e32 v8, 0
	v_mov_b32_e32 v7, 0
	v_mov_b32_e32 v10, 0
	v_mov_b32_e32 v9, 0
	s_waitcnt lgkmcnt(0)
	s_barrier
	s_add_i32 s98, s45, s69
	s_cmpk_lt_i32 s98, 0x800
	s_cbranch_scc0 .Lisel_nowarm
	s_and_b32 s99, s98, 0xff
	s_xor_b32 s100, s99, 0x1ff
	s_bitcmp1_b32 s98, 8
	s_cselect_b32 s99, s100, s99
	s_lshl_b32 s99, s99, 3
	s_lshr_b32 s98, s98, 9
	s_lshl_b32 s100, s98, 12
	s_or_b32 s99, s99, s100
	v_and_b32_e32 v85, 15, v221
	s_lshl_b32 s100, s99, 11
	s_lshr_b32 s101, s0, 3
	s_add_i32 s100, s100, s101
	v_lshl_add_u32 v86, v85, 7, s100
	global_load_dword v87, v86, s[82:83]
	s_lshl_b32 s100, s98, 19
	s_lshr_b32 s101, s0, 2
	s_add_i32 s98, s100, s101
	v_and_b32_e32 v85, 31, v221
	v_lshl_add_u32 v86, v85, 7, s98
	v_readlane_b32 s100, v239, 12
	v_readlane_b32 s101, v239, 13
	s_lshr_b32 s98, s99, 8
	s_mulk_i32 s98, 0x49
	s_lshl_b32 s98, s98, 17
	s_add_u32 s98, s98, 0x1bb00800
	s_nop 0
	global_load_dword v88, v86, s[100:101]
	s_lshl_b32 s100, s99, 9
	s_and_b32 s100, s100, 0x1e000
	s_add_u32 s98, s98, s100
	s_lshl_b32 s100, s99, 6
	s_and_b32 s100, s100, 0x200
	s_add_u32 s98, s98, s100
	v_and_b32_e32 v85, 3, v221
	v_lshl_add_u32 v86, v85, 7, s98
	v_readlane_b32 s100, v237, 5
	v_readlane_b32 s101, v237, 6
	s_nop 4
	global_load_dword v89, v86, s[100:101]
.Lisel_nowarm:
	s_cbranch_vccz .LBB0_353
	v_cmp_ge_i32_e32 vcc, s29, v221
	v_mov_b32_e32 v0, 0
	v_mov_b32_e32 v4, 0
	s_and_saveexec_b64 s[0:1], vcc
	v_lshl_add_u32 v2, v221, 2, s34
	ds_read_b32 v4, v2
	s_or_b64 exec, exec, s[0:1]
	v_or_b32_e32 v2, 64, v221
	v_cmp_ge_i32_e32 vcc, s29, v2
	s_and_saveexec_b64 s[0:1], vcc
	v_lshl_add_u32 v0, v221, 2, s34
	ds_read_b32 v0, v0 offset:256
	s_or_b64 exec, exec, s[0:1]
	v_or_b32_e32 v2, 0x80, v221
	v_cmp_ge_i32_e32 vcc, s29, v2
	v_mov_b32_e32 v5, 0
	v_mov_b32_e32 v6, 0
	s_and_saveexec_b64 s[0:1], vcc
	v_lshl_add_u32 v2, v221, 2, s34
	ds_read_b32 v6, v2 offset:512
	s_or_b64 exec, exec, s[0:1]
	v_or_b32_e32 v2, 0xc0, v221
	v_cmp_ge_i32_e32 vcc, s29, v2
	s_and_saveexec_b64 s[0:1], vcc
	v_lshl_add_u32 v2, v221, 2, s34
	ds_read_b32 v5, v2 offset:768
	s_or_b64 exec, exec, s[0:1]
	v_or_b32_e32 v2, 0x100, v221
	v_cmp_ge_i32_e32 vcc, s29, v2
	v_mov_b32_e32 v7, 0
	v_mov_b32_e32 v8, 0
	s_and_saveexec_b64 s[0:1], vcc
	v_lshl_add_u32 v2, v221, 2, s34
	ds_read_b32 v8, v2 offset:1024
	s_or_b64 exec, exec, s[0:1]
	v_or_b32_e32 v2, 0x140, v221
	v_cmp_ge_i32_e32 vcc, s29, v2
	s_and_saveexec_b64 s[0:1], vcc
	v_lshl_add_u32 v2, v221, 2, s34
	ds_read_b32 v7, v2 offset:1280
	s_or_b64 exec, exec, s[0:1]
	v_or_b32_e32 v2, 0x180, v221
	v_cmp_ge_i32_e32 vcc, s29, v2
	v_mov_b32_e32 v9, 0
	v_mov_b32_e32 v10, 0
	s_and_saveexec_b64 s[0:1], vcc
	v_lshl_add_u32 v2, v221, 2, s34
	ds_read_b32 v10, v2 offset:1536
	s_or_b64 exec, exec, s[0:1]
	v_or_b32_e32 v2, 0x1c0, v221
	v_cmp_ge_i32_e32 vcc, s29, v2
	s_and_saveexec_b64 s[0:1], vcc
	v_lshl_add_u32 v2, v221, 2, s34
	ds_read_b32 v9, v2 offset:1792
	s_or_b64 exec, exec, s[0:1]
